# GEMM1 K-loop load segments trimmed: 16 LDS-DMAs per iteration use SGPR-base + 32-bit VGPR offset form (16 v_lshl_add_u64 removed), loop-edge SALU hoisted above the closing barrier; on top of stage B
# baseline (speedup 1.0000x reference)
; #define PG8_STAGE(bufoff, gbase, voff) do { _Pragma("unroll") for (int _i = 0; _i < 2; ++_i) \
;         __builtin_amdgcn_global_load_lds((const unsigned*)((const char*)(gbase) + (voff)[_i]), (LAS unsigned*)(lds + (bufoff) + ldsw + _i * 8192), 16, 0, 0); } while (0)
; #define PG8_WAIT_V(n) asm volatile("s_waitcnt vmcnt(" #n ")" ::: "memory")
; #define PG8_BAR __builtin_amdgcn_s_barrier()
; template <class Epi, class Sched, bool ALIGN_EPI = false, bool SP2 = true>
; DI void gemm_phase(LAS unsigned char* lds, const Gemm g, const Sched& S, const Epi& E, f32x4 (&acc)[2][2][4][2]) {
;     ...
;     const int wid = __builtin_amdgcn_readfirstlane(tid >> 6), lane = tid & 63, wr = wid >> 2, wc = wid & 3, fr = lane & 15, fq = lane >> 4;
;     const int K = g.K, nt = K / BK;
;     unsigned voffA[2], voffB[2];
; #pragma unroll
;     for (int i = 0; i < 2; ++i) { int R, C; stage_rc(tid * 16 + i * 8192, R, C); const int Rb = Epi::PERM ? ((R & ~31) + perm32(R & 31)) : R;
;         voffA[i] = (unsigned)(R * K + C) * 2u; voffB[i] = (unsigned)(Rb * K + C) * 2u; }
;     const size_t kstep = (size_t)(BK * 2);
;     const size_t hstep = (size_t)HALF * K * 2;
;     const size_t tstep = 2 * hstep;
;     const unsigned ldsw = (unsigned)wid * 1024u;
;     const int aoff = lds_byte(wr * 64 + fr, fq * 8), boff = lds_byte(wc * 32 + fr, fq * 8);
;     ...
;     Unit cur, nxt; int ui = 0;
;     if (!S.next(0, cur)) return;
;     bf16x8 At[4][2], B0[2][2], B1[2][2];
;     const char* cA = (const char*)g.A + (size_t)cur.pm * tstep; const char* cB = (const char*)g.Bt + (size_t)cur.pn * tstep;
;     if constexpr (SP2) {
;         PG8_STAGE(PG8_SB(0, 0), cB, voffB); PG8_STAGE(PG8_SB(0, 1), cB + hstep, voffB); PG8_STAGE(PG8_SA(0, 0), cA, voffA); PG8_STAGE(PG8_SA(0, 1), cA + hstep, voffA);
;         if (wr == 1) PG8_BAR;
;         PG8_WAIT_V(2); PG8_BAR;
;         PG8_STAGE(PG8_SB(1, 0), cB + kstep, voffB); PG8_STAGE(PG8_SA(1, 0), cA + kstep, voffA); PG8_STAGE(PG8_SB(1, 1), cB + hstep + kstep, voffB);
;         PG8_WAIT_V(6); PG8_BAR;
.LBB0_137:
	s_add_u32 s8, s68, 0x4a80000
	s_addc_u32 s9, s69, 0
	s_add_u32 s4, s68, 0x9a80000
	s_addc_u32 s5, s69, 0
	s_add_u32 s10, s68, 0x2a80000
	s_load_dword s33, s[0:1], 0x78
	s_addc_u32 s11, s69, 0
	s_add_u32 s44, s68, 0x5a80000
	s_addc_u32 s45, s69, 0
	s_add_u32 s46, s68, 0x9aa0000
	s_addc_u32 s47, s69, 0
	s_andn2_b64 vcc, exec, s[14:15]
	s_cbranch_vccnz .LBB0_342
	v_ashrrev_i32_e32 v1, 31, v8
	v_lshrrev_b32_e32 v1, 26, v1
	v_add_u32_e32 v1, v8, v1
	v_ashrrev_i32_e32 v9, 6, v1
	v_bfe_i32 v1, v8, 27, 1
	v_lshlrev_b32_e32 v0, 4, v8
	v_lshrrev_b32_e32 v1, 22, v1
	v_add_u32_e32 v1, v0, v1
	v_and_b32_e32 v1, 0xfffffc00, v1
	v_sub_u32_e32 v1, v0, v1
	v_lshrrev_b32_e32 v2, 4, v1
	v_bitop3_b32 v1, v2, v1, 32 bitop3:0x6c
	v_ashrrev_i32_e32 v3, 31, v1
	v_lshrrev_b32_e32 v3, 26, v3
	v_add_u32_e32 v3, v1, v3
	v_lshlrev_b32_e32 v2, 3, v9
	v_ashrrev_i32_e32 v10, 6, v3
	v_and_b32_e32 v3, 0xc0, v3
	v_and_b32_e32 v2, -16, v2
	v_sub_u32_e32 v1, v1, v3
	v_mov_b32_e32 v3, 1
	v_add_u32_e32 v2, v10, v2
	v_ashrrev_i16_sdwa v1, v3, sext(v1) dst_sel:DWORD dst_unused:UNUSED_PAD src0_sel:DWORD src1_sel:BYTE_0
	v_lshlrev_b32_e32 v4, 5, v9
	v_bfe_i32 v11, v1, 0, 16
	v_lshlrev_b32_e32 v1, 1, v2
	v_lshrrev_b32_e32 v5, 2, v2
	v_and_b32_e32 v6, 3, v10
	s_mov_b32 s0, 0x1fffe0
	v_and_b32_e32 v4, 32, v4
	v_and_b32_e32 v1, 24, v1
	v_and_b32_e32 v5, 4, v5
	v_and_or_b32 v6, v2, s0, v6
	v_or3_b32 v1, v6, v5, v1
	v_add_lshl_u32 v4, v4, v11, 1
	v_add_u32_e32 v0, 0x2000, v0
	v_lshl_add_u32 v130, v1, 11, v4
	v_lshrrev_b32_e32 v1, 8, v8
	v_lshl_add_u32 v130, v1, 16, v130
	v_ashrrev_i32_e32 v1, 31, v0
	v_lshrrev_b32_e32 v1, 22, v1
	v_add_u32_e32 v1, v0, v1
	v_ashrrev_i32_e32 v12, 10, v1
	v_mul_i32_i24_e32 v1, 0x400, v12
	v_sub_u32_e32 v0, v0, v1
	v_lshrrev_b32_e32 v1, 4, v0
	v_bitop3_b32 v0, v1, v0, 32 bitop3:0x6c
	v_lshl_add_u32 v128, v2, 11, v4
	v_ashrrev_i32_e32 v2, 31, v0
	v_lshrrev_b32_e32 v2, 26, v2
	v_add_u32_e32 v2, v0, v2
	v_lshlrev_b32_e32 v1, 3, v12
	v_ashrrev_i32_e32 v13, 6, v2
	v_and_b32_e32 v2, 0xc0, v2
	v_and_b32_e32 v1, -16, v1
	v_sub_u32_e32 v0, v0, v2
	v_add_u32_e32 v1, v13, v1
	v_ashrrev_i16_sdwa v0, v3, sext(v0) dst_sel:DWORD dst_unused:UNUSED_PAD src0_sel:DWORD src1_sel:BYTE_0
	v_and_b32_e32 v3, 3, v13
	s_ashr_i32 s14, s18, 6
	s_ashr_i32 s17, s16, 31
	s_ashr_i32 s13, s12, 31
	s_ashr_i32 s19, s18, 8
	v_and_or_b32 v3, v1, s0, v3
	s_lshl_b32 s39, s14, 10
	s_lshl_b64 s[0:1], s[16:17], 19
	s_lshl_b64 s[12:13], s[12:13], 19
	s_add_u32 s30, s68, s12
	v_lshlrev_b32_e32 v4, 5, v12
	v_bfe_i32 v14, v0, 0, 16
	v_lshlrev_b32_e32 v0, 1, v1
	v_lshrrev_b32_e32 v2, 2, v1
	s_addc_u32 s31, s69, s13
	s_add_i32 s74, s39, 0
	v_and_b32_e32 v4, 32, v4
	v_and_b32_e32 v0, 24, v0
	v_and_b32_e32 v2, 4, v2
	s_add_i32 m0, s74, 0x10000
	v_or3_b32 v0, v3, v2, v0
	v_add_lshl_u32 v2, v4, v14, 1
	global_load_lds_dwordx4 v130, s[30:31]
	s_add_i32 m0, s74, 0x12000
	v_lshl_add_u32 v134, v0, 11, v2
	v_lshrrev_b32_e32 v0, 8, v8
	v_lshl_add_u32 v134, v0, 16, v134
	v_add_u32_e32 v134, 0x20000, v134
	v_add_u32_e32 v226, 0x80, v130
	v_add_u32_e32 v227, 0x80, v134
	s_add_u32 s12, s30, 0x10000
	global_load_lds_dwordx4 v134, s[30:31]
	s_addc_u32 s13, s31, 0
	s_add_i32 m0, s74, 0x14000
	v_lshl_add_u32 v132, v1, 11, v2
	global_load_lds_dwordx4 v130, s[12:13]
	s_add_i32 m0, s74, 0x16000
	s_add_u32 s0, s68, s0
	s_addc_u32 s1, s69, s1
	s_add_i32 s75, s74, 0x2000
	global_load_lds_dwordx4 v134, s[12:13]
	s_mov_b32 m0, s74
	s_add_u32 s12, s0, 0x40000
	global_load_lds_dwordx4 v128, s[0:1]
	s_mov_b32 m0, s75
	s_addc_u32 s13, s1, 0
	s_add_i32 s76, s74, 0x4000
	global_load_lds_dwordx4 v132, s[0:1]
	s_mov_b32 m0, s76
	s_add_i32 s77, s74, 0x6000
	global_load_lds_dwordx4 v128, s[12:13]
	s_mov_b32 m0, s77
	v_mov_b32_e32 v131, 0
	global_load_lds_dwordx4 v132, s[12:13]
	v_mov_b32_e32 v135, v131
	v_mov_b32_e32 v129, v131
	v_mov_b32_e32 v133, v131
	s_cmp_eq_u32 s19, 1
	s_mov_b32 s78, 0
	v_lshl_add_u64 v[6:7], s[30:31], 0, v[130:131]
	v_lshl_add_u64 v[4:5], s[30:31], 0, v[134:135]
	v_lshl_add_u64 v[0:1], s[0:1], 0, v[128:129]
	s_cselect_b64 s[12:13], -1, 0
	s_cmp_lg_u32 s19, 1
	v_lshl_add_u64 v[2:3], s[0:1], 0, v[132:133]
	s_cbranch_scc1 .LBB0_140
	s_barrier

; #define PG8_STAGE(bufoff, gbase, voff) do { _Pragma("unroll") for (int _i = 0; _i < 2; ++_i) \
;         __builtin_amdgcn_global_load_lds((const unsigned*)((const char*)(gbase) + (voff)[_i]), (LAS unsigned*)(lds + (bufoff) + ldsw + _i * 8192), 16, 0, 0); } while (0)
; #define PG8_LDA(dst, b, h) do { _Pragma("unroll") for (int m = 0; m < 4; ++m) _Pragma("unroll") for (int k = 0; k < 2; ++k) dst[m][k] = *(const LAS bf16x8*)(lds + PG8_SA(b, h) + aoff + m * 2048 + k * 1024); } while (0)
; #define PG8_LDB(dst, b, h) do { _Pragma("unroll") for (int n = 0; n < 2; ++n) _Pragma("unroll") for (int k = 0; k < 2; ++k) dst[n][k] = *(const LAS bf16x8*)(lds + PG8_SB(b, h) + boff + n * 2048 + k * 1024); } while (0)
; #define PG8_MMA(ai, bj, At, Bt) do { __builtin_amdgcn_s_setprio(1); _Pragma("unroll") for (int m = 0; m < 4; ++m) _Pragma("unroll") for (int n = 0; n < 2; ++n) _Pragma("unroll") for (int k = 0; k < 2; ++k) \
;         acc[ai][bj][m][n] = __builtin_amdgcn_mfma_f32_16x16x32_bf16(Bt[n][k], At[m][k], acc[ai][bj][m][n], 0, 0, 0); __builtin_amdgcn_s_setprio(0); } while (0)
; #define PG8_WAIT_V(n) asm volatile("s_waitcnt vmcnt(" #n ")" ::: "memory")
; #define PG8_WAIT_L(n) asm volatile("s_waitcnt lgkmcnt(" #n ")" ::: "memory")
; #define PG8_BAR __builtin_amdgcn_s_barrier()
; template <class Epi, class Sched, bool ALIGN_EPI = false, bool SP2 = true>
; DI void gemm_phase(LAS unsigned char* lds, const Gemm g, const Sched& S, const Epi& E, f32x4 (&acc)[2][2][4][2]) {
;     ...
;         for (int t = 0; t < nt; t += 2) {
;             const bool last = (t == nt - 2);
;             const char* a1 = cA + (size_t)(t + 1) * kstep;
;             const char* a2 = last ? nA : cA + (size_t)(t + 2) * kstep; const char* b2 = last ? nB : cB + (size_t)(t + 2) * kstep;
;             const char* a3 = a2 + kstep; const char* b3 = b2 + kstep;
;             if constexpr (SP2) {
;             PG8_LDB(B0, 0, 0); PG8_LDB(B1, 0, 1); PG8_SCHED; PG8_LDA(At, 0, 0); PG8_STAGE(PG8_SA(1, 1), a1 + hstep, voffA);
;             PG8_WAIT_V(8); PG8_WAIT_L(0); PG8_BAR; PG8_MMA(0, 0, At, B0); PG8_MMA(0, 1, At, B1); PG8_BAR; PG8_SCHED;
;             PG8_LDA(At, 0, 1); PG8_STAGE(PG8_SB(0, 0), b2, voffB); PG8_STAGE(PG8_SB(0, 1), b2 + hstep, voffB); PG8_STAGE(PG8_SA(0, 0), a2, voffA);
;             PG8_WAIT_V(8); PG8_WAIT_L(0); PG8_BAR; PG8_MMA(1, 0, At, B0); PG8_MMA(1, 1, At, B1); PG8_BAR; PG8_SCHED;
.LBB0_159:
	ds_read_b128 v[150:153], v164
	ds_read_b128 v[154:157], v164 offset:1024
	ds_read_b128 v[158:161], v164 offset:2048
	ds_read_b128 v[168:171], v164 offset:3072
	ds_read_b128 v[172:175], v165
	ds_read_b128 v[180:183], v165 offset:1024
	ds_read_b128 v[184:187], v165 offset:2048
	ds_read_b128 v[188:191], v165 offset:3072
	s_add_u32 s30, s0, 0xfffc0080
	s_addc_u32 s31, s1, -1
	s_cmp_eq_u32 s62, 12
	s_cselect_b32 s35, s25, s31
	s_cselect_b32 s34, s52, s30
	s_cselect_b32 s31, s23, s55
	s_cselect_b32 s30, s53, s54
	s_add_i32 m0, s74, 0xc000
	ds_read_b128 v[192:195], v166
	ds_read_b128 v[196:199], v166 offset:1024
	ds_read_b128 v[202:205], v166 offset:2048
	ds_read_b128 v[206:209], v166 offset:3072
	ds_read_b128 v[210:213], v166 offset:4096
	ds_read_b128 v[214:217], v166 offset:5120
	ds_read_b128 v[218:221], v166 offset:6144
	ds_read_b128 v[222:225], v166 offset:7168
	global_load_lds_dwordx4 v146, s[0:1]
	s_add_i32 m0, s74, 0xe000
	s_nop 0
	global_load_lds_dwordx4 v148, s[0:1]
	s_waitcnt vmcnt(8)
	s_waitcnt lgkmcnt(0)
	s_barrier
	s_setprio 1
	s_waitcnt lgkmcnt(0)
	v_mfma_f32_16x16x32_bf16 v[124:127], v[150:153], v[192:195], v[124:127]
	v_mfma_f32_16x16x32_bf16 v[120:123], v[158:161], v[192:195], v[120:123]
	v_mfma_f32_16x16x32_bf16 v[108:111], v[150:153], v[202:205], v[108:111]
	v_mfma_f32_16x16x32_bf16 v[104:107], v[158:161], v[202:205], v[104:107]
	v_mfma_f32_16x16x32_bf16 v[92:95], v[150:153], v[210:213], v[92:95]
	v_mfma_f32_16x16x32_bf16 v[88:91], v[158:161], v[210:213], v[88:91]
	v_mfma_f32_16x16x32_bf16 v[76:79], v[150:153], v[218:221], v[76:79]
	v_mfma_f32_16x16x32_bf16 v[72:75], v[158:161], v[218:221], v[72:75]
	v_mfma_f32_16x16x32_bf16 v[124:127], v[154:157], v[196:199], v[124:127]
	v_mfma_f32_16x16x32_bf16 v[120:123], v[168:171], v[196:199], v[120:123]
	v_mfma_f32_16x16x32_bf16 v[108:111], v[154:157], v[206:209], v[108:111]
	v_mfma_f32_16x16x32_bf16 v[104:107], v[168:171], v[206:209], v[104:107]
	v_mfma_f32_16x16x32_bf16 v[92:95], v[154:157], v[214:217], v[92:95]
	v_mfma_f32_16x16x32_bf16 v[88:91], v[168:171], v[214:217], v[88:91]
	v_mfma_f32_16x16x32_bf16 v[76:79], v[154:157], v[222:225], v[76:79]
	v_mfma_f32_16x16x32_bf16 v[72:75], v[168:171], v[222:225], v[72:75]
	s_setprio 0
	s_setprio 1
	v_mfma_f32_16x16x32_bf16 v[116:119], v[172:175], v[192:195], v[116:119]
	v_mfma_f32_16x16x32_bf16 v[112:115], v[184:187], v[192:195], v[112:115]
	v_mfma_f32_16x16x32_bf16 v[100:103], v[172:175], v[202:205], v[100:103]
	v_mfma_f32_16x16x32_bf16 v[96:99], v[184:187], v[202:205], v[96:99]
	v_mfma_f32_16x16x32_bf16 v[84:87], v[172:175], v[210:213], v[84:87]
	v_mfma_f32_16x16x32_bf16 v[80:83], v[184:187], v[210:213], v[80:83]
	v_mfma_f32_16x16x32_bf16 v[68:71], v[172:175], v[218:221], v[68:71]
	v_mfma_f32_16x16x32_bf16 v[64:67], v[184:187], v[218:221], v[64:67]
	v_mfma_f32_16x16x32_bf16 v[116:119], v[180:183], v[196:199], v[116:119]
	v_mfma_f32_16x16x32_bf16 v[112:115], v[188:191], v[196:199], v[112:115]
	v_mfma_f32_16x16x32_bf16 v[100:103], v[180:183], v[206:209], v[100:103]
	v_mfma_f32_16x16x32_bf16 v[96:99], v[188:191], v[206:209], v[96:99]
	v_mfma_f32_16x16x32_bf16 v[84:87], v[180:183], v[214:217], v[84:87]
	v_mfma_f32_16x16x32_bf16 v[80:83], v[188:191], v[214:217], v[80:83]
	v_mfma_f32_16x16x32_bf16 v[68:71], v[180:183], v[222:225], v[68:71]
	v_mfma_f32_16x16x32_bf16 v[64:67], v[188:191], v[222:225], v[64:67]
	s_setprio 0
	s_barrier
	s_add_i32 s63, s82, s39
	s_mov_b32 m0, s63
	ds_read_b128 v[192:195], v166 offset:16384
	ds_read_b128 v[196:199], v166 offset:17408
	ds_read_b128 v[202:205], v166 offset:18432
	ds_read_b128 v[206:209], v166 offset:19456
	ds_read_b128 v[210:213], v166 offset:20480
	ds_read_b128 v[214:217], v166 offset:21504
	ds_read_b128 v[218:221], v166 offset:22528
	ds_read_b128 v[222:225], v166 offset:23552
	global_load_lds_dwordx4 v130, s[30:31]
	s_add_i32 m0, s63, 0x2000
	s_add_u32 s72, s30, 0x10000
	s_addc_u32 s73, s31, 0
	s_add_i32 s63, s83, s39
	global_load_lds_dwordx4 v134, s[30:31]
	s_mov_b32 m0, s63
	s_nop 0
	global_load_lds_dwordx4 v130, s[72:73]
	s_add_i32 m0, s63, 0x2000
	s_nop 0
	global_load_lds_dwordx4 v134, s[72:73]
	s_mov_b32 m0, s74
	s_nop 0
	global_load_lds_dwordx4 v128, s[34:35]
	s_mov_b32 m0, s75
	s_nop 0
	global_load_lds_dwordx4 v132, s[34:35]
	s_waitcnt vmcnt(8)
	s_waitcnt lgkmcnt(0)
	s_barrier
	s_setprio 1
	s_waitcnt lgkmcnt(0)
	v_mfma_f32_16x16x32_bf16 v[60:63], v[150:153], v[192:195], v[60:63]
	v_mfma_f32_16x16x32_bf16 v[56:59], v[158:161], v[192:195], v[56:59]
	v_mfma_f32_16x16x32_bf16 v[44:47], v[150:153], v[202:205], v[44:47]
	v_mfma_f32_16x16x32_bf16 v[40:43], v[158:161], v[202:205], v[40:43]
	v_mfma_f32_16x16x32_bf16 v[28:31], v[150:153], v[210:213], v[28:31]
	v_mfma_f32_16x16x32_bf16 v[24:27], v[158:161], v[210:213], v[24:27]
	v_mfma_f32_16x16x32_bf16 v[12:15], v[150:153], v[218:221], v[12:15]
	v_mfma_f32_16x16x32_bf16 v[8:11], v[158:161], v[218:221], v[8:11]
	v_mfma_f32_16x16x32_bf16 v[60:63], v[154:157], v[196:199], v[60:63]
	v_mfma_f32_16x16x32_bf16 v[56:59], v[168:171], v[196:199], v[56:59]
	v_mfma_f32_16x16x32_bf16 v[44:47], v[154:157], v[206:209], v[44:47]
	v_mfma_f32_16x16x32_bf16 v[40:43], v[168:171], v[206:209], v[40:43]
	v_mfma_f32_16x16x32_bf16 v[28:31], v[154:157], v[214:217], v[28:31]
	v_mfma_f32_16x16x32_bf16 v[24:27], v[168:171], v[214:217], v[24:27]
	v_mfma_f32_16x16x32_bf16 v[12:15], v[154:157], v[222:225], v[12:15]
	v_mfma_f32_16x16x32_bf16 v[8:11], v[168:171], v[222:225], v[8:11]
	s_setprio 0
	s_setprio 1
	v_mfma_f32_16x16x32_bf16 v[52:55], v[172:175], v[192:195], v[52:55]
	v_mfma_f32_16x16x32_bf16 v[48:51], v[184:187], v[192:195], v[48:51]
	v_mfma_f32_16x16x32_bf16 v[36:39], v[172:175], v[202:205], v[36:39]
	v_mfma_f32_16x16x32_bf16 v[32:35], v[184:187], v[202:205], v[32:35]
	v_mfma_f32_16x16x32_bf16 v[20:23], v[172:175], v[210:213], v[20:23]
	v_mfma_f32_16x16x32_bf16 v[16:19], v[184:187], v[210:213], v[16:19]
	v_mfma_f32_16x16x32_bf16 v[4:7], v[172:175], v[218:221], v[4:7]
	v_mfma_f32_16x16x32_bf16 v[0:3], v[184:187], v[218:221], v[0:3]
	v_mfma_f32_16x16x32_bf16 v[52:55], v[180:183], v[196:199], v[52:55]
	v_mfma_f32_16x16x32_bf16 v[48:51], v[188:191], v[196:199], v[48:51]
	v_mfma_f32_16x16x32_bf16 v[36:39], v[180:183], v[206:209], v[36:39]
	v_mfma_f32_16x16x32_bf16 v[32:35], v[188:191], v[206:209], v[32:35]
	v_mfma_f32_16x16x32_bf16 v[20:23], v[180:183], v[214:217], v[20:23]
	v_mfma_f32_16x16x32_bf16 v[16:19], v[188:191], v[214:217], v[16:19]
	v_mfma_f32_16x16x32_bf16 v[4:7], v[180:183], v[222:225], v[4:7]
	v_mfma_f32_16x16x32_bf16 v[0:3], v[188:191], v[222:225], v[0:3]
	s_setprio 0
	s_barrier
; #define PG8_STAGE(bufoff, gbase, voff) do { _Pragma("unroll") for (int _i = 0; _i < 2; ++_i) \
;         __builtin_amdgcn_global_load_lds((const unsigned*)((const char*)(gbase) + (voff)[_i]), (LAS unsigned*)(lds + (bufoff) + ldsw + _i * 8192), 16, 0, 0); } while (0)
; #define PG8_LDA(dst, b, h) do { _Pragma("unroll") for (int m = 0; m < 4; ++m) _Pragma("unroll") for (int k = 0; k < 2; ++k) dst[m][k] = *(const LAS bf16x8*)(lds + PG8_SA(b, h) + aoff + m * 2048 + k * 1024); } while (0)
; #define PG8_LDB(dst, b, h) do { _Pragma("unroll") for (int n = 0; n < 2; ++n) _Pragma("unroll") for (int k = 0; k < 2; ++k) dst[n][k] = *(const LAS bf16x8*)(lds + PG8_SB(b, h) + boff + n * 2048 + k * 1024); } while (0)
; #define PG8_MMA(ai, bj, At, Bt) do { __builtin_amdgcn_s_setprio(1); _Pragma("unroll") for (int m = 0; m < 4; ++m) _Pragma("unroll") for (int n = 0; n < 2; ++n) _Pragma("unroll") for (int k = 0; k < 2; ++k) \
;         acc[ai][bj][m][n] = __builtin_amdgcn_mfma_f32_16x16x32_bf16(Bt[n][k], At[m][k], acc[ai][bj][m][n], 0, 0, 0); __builtin_amdgcn_s_setprio(0); } while (0)
; #define PG8_WAIT_V(n) asm volatile("s_waitcnt vmcnt(" #n ")" ::: "memory")
; #define PG8_WAIT_L(n) asm volatile("s_waitcnt lgkmcnt(" #n ")" ::: "memory")
; #define PG8_BAR __builtin_amdgcn_s_barrier()
; #define PG8_SCHED __builtin_amdgcn_sched_barrier(0)
; template <class Epi, class Sched, bool ALIGN_EPI = false, bool SP2 = true>
; DI void gemm_phase(LAS unsigned char* lds, const Gemm g, const Sched& S, const Epi& E, f32x4 (&acc)[2][2][4][2]) {
;     ...
;             PG8_LDB(B0, 1, 0); PG8_LDB(B1, 1, 1); PG8_SCHED; PG8_LDA(At, 1, 0); PG8_STAGE(PG8_SA(0, 1), a2 + hstep, voffA);
;             PG8_WAIT_V(8); PG8_WAIT_L(0); PG8_BAR; PG8_MMA(0, 0, At, B0); PG8_MMA(0, 1, At, B1); PG8_BAR; PG8_SCHED;
;             PG8_LDA(At, 1, 1); PG8_STAGE(PG8_SB(1, 0), b3, voffB); PG8_STAGE(PG8_SB(1, 1), b3 + hstep, voffB); PG8_STAGE(PG8_SA(1, 0), a3, voffA);
;             PG8_WAIT_V(8); PG8_WAIT_L(0); PG8_BAR; PG8_MMA(1, 0, At, B0); PG8_MMA(1, 1, At, B1); PG8_BAR; PG8_SCHED;
	s_add_i32 s63, 0, 0x18000
	s_add_i32 s64, 0, 0x1c000
	v_add_u32_e32 v168, s63, v143
	v_add_u32_e32 v178, s64, v143
	ds_read_b128 v[150:153], v168
	ds_read_b128 v[154:157], v168 offset:1024
	ds_read_b128 v[158:161], v168 offset:2048
	ds_read_b128 v[168:171], v168 offset:3072
	ds_read_b128 v[172:175], v178
	ds_read_b128 v[180:183], v178 offset:1024
	ds_read_b128 v[184:187], v178 offset:2048
	ds_read_b128 v[188:191], v178 offset:3072
	s_add_u32 s34, s34, 0x40000
	s_addc_u32 s35, s35, 0
	s_mov_b32 m0, s76
	ds_read_b128 v[192:195], v166 offset:32768
	ds_read_b128 v[196:199], v166 offset:33792
	ds_read_b128 v[202:205], v166 offset:34816
	ds_read_b128 v[206:209], v166 offset:35840
	ds_read_b128 v[210:213], v166 offset:36864
	ds_read_b128 v[214:217], v166 offset:37888
	ds_read_b128 v[218:221], v166 offset:38912
	ds_read_b128 v[222:225], v166 offset:39936
	global_load_lds_dwordx4 v128, s[34:35]
	s_mov_b32 m0, s77
	s_nop 0
	global_load_lds_dwordx4 v132, s[34:35]
	s_waitcnt vmcnt(8)
	s_waitcnt lgkmcnt(0)
	s_barrier
	s_setprio 1
	s_waitcnt lgkmcnt(0)
	v_mfma_f32_16x16x32_bf16 v[124:127], v[150:153], v[192:195], v[124:127]
	v_mfma_f32_16x16x32_bf16 v[120:123], v[158:161], v[192:195], v[120:123]
	v_mfma_f32_16x16x32_bf16 v[108:111], v[150:153], v[202:205], v[108:111]
	v_mfma_f32_16x16x32_bf16 v[104:107], v[158:161], v[202:205], v[104:107]
	v_mfma_f32_16x16x32_bf16 v[92:95], v[150:153], v[210:213], v[92:95]
	v_mfma_f32_16x16x32_bf16 v[88:91], v[158:161], v[210:213], v[88:91]
	v_mfma_f32_16x16x32_bf16 v[76:79], v[150:153], v[218:221], v[76:79]
	v_mfma_f32_16x16x32_bf16 v[72:75], v[158:161], v[218:221], v[72:75]
	v_mfma_f32_16x16x32_bf16 v[124:127], v[154:157], v[196:199], v[124:127]
	v_mfma_f32_16x16x32_bf16 v[120:123], v[168:171], v[196:199], v[120:123]
	v_mfma_f32_16x16x32_bf16 v[108:111], v[154:157], v[206:209], v[108:111]
	v_mfma_f32_16x16x32_bf16 v[104:107], v[168:171], v[206:209], v[104:107]
	v_mfma_f32_16x16x32_bf16 v[92:95], v[154:157], v[214:217], v[92:95]
	v_mfma_f32_16x16x32_bf16 v[88:91], v[168:171], v[214:217], v[88:91]
	v_mfma_f32_16x16x32_bf16 v[76:79], v[154:157], v[222:225], v[76:79]
	v_mfma_f32_16x16x32_bf16 v[72:75], v[168:171], v[222:225], v[72:75]
	s_setprio 0
	s_setprio 1
	v_mfma_f32_16x16x32_bf16 v[116:119], v[172:175], v[192:195], v[116:119]
	v_mfma_f32_16x16x32_bf16 v[112:115], v[184:187], v[192:195], v[112:115]
	v_mfma_f32_16x16x32_bf16 v[100:103], v[172:175], v[202:205], v[100:103]
	v_mfma_f32_16x16x32_bf16 v[96:99], v[184:187], v[202:205], v[96:99]
	v_mfma_f32_16x16x32_bf16 v[84:87], v[172:175], v[210:213], v[84:87]
	v_mfma_f32_16x16x32_bf16 v[80:83], v[184:187], v[210:213], v[80:83]
	v_mfma_f32_16x16x32_bf16 v[68:71], v[172:175], v[218:221], v[68:71]
	v_mfma_f32_16x16x32_bf16 v[64:67], v[184:187], v[218:221], v[64:67]
	v_mfma_f32_16x16x32_bf16 v[116:119], v[180:183], v[196:199], v[116:119]
	v_mfma_f32_16x16x32_bf16 v[112:115], v[188:191], v[196:199], v[112:115]
	v_mfma_f32_16x16x32_bf16 v[100:103], v[180:183], v[206:209], v[100:103]
	v_mfma_f32_16x16x32_bf16 v[96:99], v[188:191], v[206:209], v[96:99]
	v_mfma_f32_16x16x32_bf16 v[84:87], v[180:183], v[214:217], v[84:87]
	v_mfma_f32_16x16x32_bf16 v[80:83], v[188:191], v[214:217], v[80:83]
	v_mfma_f32_16x16x32_bf16 v[68:71], v[180:183], v[222:225], v[68:71]
	v_mfma_f32_16x16x32_bf16 v[64:67], v[188:191], v[222:225], v[64:67]
	s_setprio 0
	s_barrier
	s_add_u32 s72, s34, 0xfffc0080
	s_addc_u32 s73, s35, -1
	s_add_i32 s34, s63, s39
	s_mov_b32 m0, s34
	ds_read_b128 v[192:195], v166 offset:49152
	ds_read_b128 v[196:199], v166 offset:50176
	ds_read_b128 v[202:205], v166 offset:51200
	ds_read_b128 v[206:209], v166 offset:52224
	ds_read_b128 v[210:213], v166 offset:53248
	ds_read_b128 v[214:217], v166 offset:54272
	ds_read_b128 v[218:221], v166 offset:55296
	ds_read_b128 v[222:225], v166 offset:56320
	global_load_lds_dwordx4 v226, s[30:31]
	s_add_i32 m0, s34, 0x2000
	s_add_i32 s34, s64, s39
	global_load_lds_dwordx4 v227, s[30:31]
	s_add_u32 s30, s30, 0x10080
	s_addc_u32 s31, s31, 0
	s_mov_b32 m0, s34
	s_nop 0
	global_load_lds_dwordx4 v130, s[30:31]
	s_add_i32 m0, s34, 0x2000
	s_nop 0
	global_load_lds_dwordx4 v134, s[30:31]
	s_mov_b32 m0, s80
	s_nop 0
	global_load_lds_dwordx4 v128, s[72:73]
	s_mov_b32 m0, s81
	s_nop 0
	global_load_lds_dwordx4 v132, s[72:73]
	s_waitcnt vmcnt(8)
	s_waitcnt lgkmcnt(0)
	s_barrier
	s_setprio 1
	s_waitcnt lgkmcnt(0)
	v_mfma_f32_16x16x32_bf16 v[60:63], v[150:153], v[192:195], v[60:63]
	v_mfma_f32_16x16x32_bf16 v[56:59], v[158:161], v[192:195], v[56:59]
	v_mfma_f32_16x16x32_bf16 v[44:47], v[150:153], v[202:205], v[44:47]
	v_mfma_f32_16x16x32_bf16 v[40:43], v[158:161], v[202:205], v[40:43]
	v_mfma_f32_16x16x32_bf16 v[28:31], v[150:153], v[210:213], v[28:31]
	v_mfma_f32_16x16x32_bf16 v[24:27], v[158:161], v[210:213], v[24:27]
	v_mfma_f32_16x16x32_bf16 v[12:15], v[150:153], v[218:221], v[12:15]
	v_mfma_f32_16x16x32_bf16 v[8:11], v[158:161], v[218:221], v[8:11]
	v_mfma_f32_16x16x32_bf16 v[60:63], v[154:157], v[196:199], v[60:63]
	v_mfma_f32_16x16x32_bf16 v[56:59], v[168:171], v[196:199], v[56:59]
	v_mfma_f32_16x16x32_bf16 v[44:47], v[154:157], v[206:209], v[44:47]
	v_mfma_f32_16x16x32_bf16 v[40:43], v[168:171], v[206:209], v[40:43]
	v_mfma_f32_16x16x32_bf16 v[28:31], v[154:157], v[214:217], v[28:31]
	v_mfma_f32_16x16x32_bf16 v[24:27], v[168:171], v[214:217], v[24:27]
	v_mfma_f32_16x16x32_bf16 v[12:15], v[154:157], v[222:225], v[12:15]
	v_mfma_f32_16x16x32_bf16 v[8:11], v[168:171], v[222:225], v[8:11]
	s_setprio 0
	s_setprio 1
	v_mfma_f32_16x16x32_bf16 v[52:55], v[172:175], v[192:195], v[52:55]
	v_mfma_f32_16x16x32_bf16 v[48:51], v[184:187], v[192:195], v[48:51]
	v_mfma_f32_16x16x32_bf16 v[36:39], v[172:175], v[202:205], v[36:39]
	v_mfma_f32_16x16x32_bf16 v[32:35], v[184:187], v[202:205], v[32:35]
	v_mfma_f32_16x16x32_bf16 v[20:23], v[172:175], v[210:213], v[20:23]
	v_mfma_f32_16x16x32_bf16 v[16:19], v[184:187], v[210:213], v[16:19]
	v_mfma_f32_16x16x32_bf16 v[4:7], v[172:175], v[218:221], v[4:7]
	v_mfma_f32_16x16x32_bf16 v[0:3], v[184:187], v[218:221], v[0:3]
	v_mfma_f32_16x16x32_bf16 v[52:55], v[180:183], v[196:199], v[52:55]
	v_mfma_f32_16x16x32_bf16 v[48:51], v[188:191], v[196:199], v[48:51]
	v_mfma_f32_16x16x32_bf16 v[36:39], v[180:183], v[206:209], v[36:39]
	v_mfma_f32_16x16x32_bf16 v[32:35], v[188:191], v[206:209], v[32:35]
	v_mfma_f32_16x16x32_bf16 v[20:23], v[180:183], v[214:217], v[20:23]
	v_mfma_f32_16x16x32_bf16 v[16:19], v[188:191], v[214:217], v[16:19]
	v_mfma_f32_16x16x32_bf16 v[4:7], v[180:183], v[222:225], v[4:7]
	v_mfma_f32_16x16x32_bf16 v[0:3], v[188:191], v[222:225], v[0:3]
	s_add_i32 s62, s62, 2
	s_add_u32 s0, s0, 0x100
	s_addc_u32 s1, s1, 0
	s_add_u32 s54, s54, 0x100
	s_addc_u32 s55, s55, 0
	s_cmp_gt_u32 s62, 13
	s_setprio 0
	s_barrier
	s_cbranch_scc0 .LBB0_159
	s_and_b64 vcc, exec, s[16:17]
	s_cbranch_vccz .LBB0_162
	s_barrier
